# in-proj tiles of prompt panels 254/255 deferred past grid barrier 2 (run by workgroups 160..181 before they join the attention queue; consumers wait on a counter); in-proj is exactly 11 full rounds; k
# baseline (speedup 1.0000x reference)
.LBB0_151:
	s_or_b64 exec, exec, s[0:1]
	s_waitcnt vmcnt(1)
	v_writelane_b32 v252, s44, 20
	s_waitcnt lgkmcnt(0)
	s_barrier
	v_writelane_b32 v252, s45, 21
	s_mov_b32 s99, 0
	s_mov_b32 s100, s2
	s_movk_i32 s101, 0xb00
.Lp1_entry:
	s_add_u32 s18, s80, 0x1800
	s_addc_u32 s19, s81, 0
	v_mov_b32_e32 v10, v0
	s_cmp_lt_i32 s100, s101
	s_cselect_b64 s[0:1], -1, 0
	s_and_b64 vcc, exec, s[0:1]
	v_readfirstlane_b32 s16, v10
	s_cbranch_vccz .LBB0_153
	s_cmp_lg_u32 s99, 0
	s_cbranch_scc1 .Lp1_first2
	s_and_b32 s4, s100, 7
	s_mulk_i32 s4, 0x160
	s_lshr_b32 s3, s100, 3
	s_add_i32 s4, s4, s3
	s_branch .Lp1_first_done
.Lp1_first2:
	s_sub_i32 s3, s100, 0xb00
	s_lshr_b32 s4, s3, 1
	s_lshl_b32 s4, s4, 2
	s_and_b32 s3, s3, 1
	s_add_i32 s4, s4, s3
	s_addk_i32 s4, 0xad6
.Lp1_first_done:
	s_mul_hi_i32 s3, s4, 0x2e8ba2e9
	s_lshr_b32 s5, s3, 31
	s_ashr_i32 s3, s3, 3
	s_add_i32 s3, s3, s5
	s_lshl_b32 s6, s3, 2
	s_sub_i32 s5, 0x102, s6
	s_mul_i32 s3, s3, 44
	s_min_u32 s7, s5, 4
	s_sub_i32 s3, s4, s3
	s_sext_i32_i8 s4, s3
	v_cvt_f32_ubyte0_e32 v3, s7
	v_cvt_f32_i32_e32 v2, s4
	v_rcp_iflag_f32_e32 v4, v3
	s_ashr_i32 s4, s4, 30
	s_or_b32 s8, s4, 1
	v_mul_f32_e32 v4, v2, v4
	v_trunc_f32_e32 v4, v4
	v_fma_f32 v2, -v4, v3, v2
	v_cvt_i32_f32_e32 v4, v4
	v_cmp_ge_f32_e64 s[4:5], |v2|, v3
	s_and_b64 s[4:5], s[4:5], exec
	s_cselect_b32 s4, s8, 0
	v_readfirstlane_b32 s5, v4
	s_add_i32 s5, s5, s4
	s_sext_i32_i8 s4, s5
	s_mul_i32 s5, s5, s7
	s_sub_i32 s3, s3, s5
	s_sext_i32_i8 s3, s3
	s_add_i32 s8, s6, s3

.LBB0_156:
	s_add_u32 s12, s80, 0x1000
	s_mov_b64 s[14:15], 0x80
	s_addc_u32 s13, s81, 0
	s_and_b32 s3, s0, 3
	s_add_i32 m0, s93, 0x18000
	v_lshl_add_u64 v[8:9], v[8:9], 0, s[14:15]
	s_lshl_b32 s97, s1, 6
	s_lshl_b32 s1, s1, 13
	s_lshl_b32 s5, s3, 5
	s_lshl_b32 s17, s3, 12
	s_waitcnt vmcnt(2)
	s_barrier
	global_load_lds_dwordx4 v[8:9], off
	v_lshl_add_u64 v[6:7], v[6:7], 0, s[14:15]
	s_add_i32 m0, s93, 0x1a000
	s_add_i32 s85, s93, 0x8000
	s_add_i32 s3, s93, 0xa000
	global_load_lds_dwordx4 v[6:7], off
	v_lshl_add_u64 v[2:3], v[2:3], 0, s[14:15]
	s_mov_b32 m0, s85
	s_add_u32 s20, s70, 0x40080
	global_load_lds_dwordx4 v[2:3], off
	v_lshl_add_u64 v[2:3], v[4:5], 0, s[14:15]
	s_mov_b32 m0, s3
	s_addc_u32 s21, s71, 0
	global_load_lds_dwordx4 v[2:3], off
	s_add_i32 m0, s93, 0x1c000
	v_lshl_add_u64 v[2:3], s[20:21], 0, v[170:171]
	global_load_lds_dwordx4 v[2:3], off
	v_lshl_add_u64 v[2:3], s[20:21], 0, v[174:175]
	s_add_i32 m0, s93, 0x1e000
	v_bfe_u32 v17, v10, 4, 2
	global_load_lds_dwordx4 v[2:3], off
	v_and_b32_e32 v167, 15, v10
	v_lshlrev_b32_e32 v18, 4, v17
	v_lshlrev_b32_e32 v3, 2, v10
	v_lshl_or_b32 v2, v167, 6, v18
	v_and_b32_e32 v3, 32, v3
	s_cmpk_lt_u32 s16, 0x100
	v_bitop3_b32 v206, v2, s17, v3 bitop3:0xde
	s_cselect_b64 s[16:17], -1, 0
	s_lshl_b32 s0, s0, 4
	s_and_b32 s20, s0, 16
	v_lshlrev_b32_e32 v5, 2, v17
	v_bitop3_b32 v4, v2, s1, v3 bitop3:0xde
	v_or_b32_e32 v2, s20, v5
	v_lshlrev_b32_e32 v176, 1, v2
	v_lshlrev_b32_e32 v2, 3, v2
	v_mov_b32_e32 v3, v177
	v_lshl_add_u64 v[178:179], s[18:19], 0, v[2:3]
	v_and_b32_e32 v2, 16, v10
	v_add_u32_e32 v3, 28, v5
	v_cmp_eq_u32_e32 vcc, 0, v2
	s_and_b32 s54, s5, 64
	s_lshl_b32 s0, s54, 1
	v_cndmask_b32_e32 v2, v3, v5, vcc
	v_add_u32_e32 v184, s20, v2
	v_lshlrev_b32_e32 v2, 14, v11
	v_and_b32_e32 v2, 0xffff8000, v2
	v_lshl_add_u32 v2, v12, 11, v2
	v_and_b32_e32 v3, 1, v11
	v_lshl_or_b32 v2, v3, 6, v2
	s_mov_b64 s[18:19], s[48:49]
	v_lshl_add_u32 v186, v13, 1, v2
	v_lshlrev_b32_e32 v2, 14, v14
	s_add_u32 s0, s18, s0
	v_and_b32_e32 v2, 0xffff8000, v2
	s_waitcnt vmcnt(0)
	v_lshl_or_b32 v207, v17, 3, s5
	s_addc_u32 s1, s19, 0
	v_lshl_add_u32 v2, v15, 11, v2
	v_and_b32_e32 v3, 1, v14
	v_lshl_add_u64 v[180:181], s[0:1], 0, v[176:177]
	v_lshlrev_b32_e32 v176, 1, v207
	v_lshl_or_b32 v2, v3, 6, v2
	s_add_i32 s86, 0, 0x10000
	s_add_i32 s87, 0, 0x14000
	v_or_b32_e32 v208, 0x410, v167
	v_or_b32_e32 v209, 0x420, v167
	v_lshl_add_u64 v[182:183], s[52:53], 0, v[176:177]
	s_or_b32 s56, s54, 0x80
	v_mov_b32_e32 v187, v177
	v_lshl_add_u32 v188, v16, 1, v2
	v_mov_b32_e32 v189, v177
	v_mov_b32_e32 v190, s101
	v_mov_b32_e32 v191, 0
	v_add_u32_e32 v192, -1, v190
	v_mov_b32_e32 v193, 0
	v_add_u32_e32 v210, s86, v206
	v_add_u32_e32 v211, s87, v206
	v_add_u32_e32 v212, 0, v4
	s_mov_b32 s19, 0xffff
	s_mov_b32 s57, 0x10100
	s_movk_i32 s84, 0x7cf
	s_mov_b32 s18, 0x3e38aa3b
	s_mov_b64 s[20:21], 0x1dc87800
	s_mov_b64 s[22:23], 0x20000
	s_mov_b64 s[24:25], 0x24000
	s_mov_b64 s[26:27], 0x28000
	s_mov_b64 s[28:29], 0x2c000
	s_mov_b32 s92, 0
	s_barrier
	s_branch .LBB0_159

.LBB0_159:
	s_add_i32 s92, s92, 1
	s_mul_i32 s0, s92, s90
	s_mul_hi_u32 s1, s92, s82
	s_add_i32 s1, s1, s0
	s_mul_i32 s0, s92, s82
	s_add_u32 s58, s0, s100
	s_addc_u32 s59, s1, s47
	v_cmp_gt_i64_e32 vcc, s[58:59], v[192:193]
	v_cmp_lt_i64_e64 s[0:1], s[58:59], v[190:191]
	s_cbranch_vccnz .LBB0_165
	s_and_b32 s33, s58, 7
	s_mulk_i32 s33, 0x160
	s_lshr_b32 s5, s58, 3
	s_add_i32 s5, s33, s5
	s_sub_i32 s30, s5, 0xad4
	s_cmp_lt_i32 s30, 0
	s_cbranch_scc1 .Lp1_next_done
	s_add_i32 s5, s5, 22
	s_cmp_gt_i32 s30, 21
	s_cbranch_scc1 .Lp1_next_done
	s_lshr_b32 s31, s30, 1
	s_lshl_b32 s31, s31, 2
	s_and_b32 s30, s30, 1
	s_add_i32 s5, s31, s30
	s_addk_i32 s5, 0xad4
.Lp1_next_done:
	s_mul_hi_i32 s30, s5, 0x2e8ba2e9
	s_lshr_b32 s31, s30, 31
	s_ashr_i32 s30, s30, 3
	s_add_i32 s30, s30, s31
	s_lshl_b32 s31, s30, 2
	s_sub_i32 s33, 0x102, s31
	s_min_i32 s33, s33, 4
	s_abs_i32 s34, s33
	v_cvt_f32_u32_e32 v2, s34
	s_sub_i32 s36, 0, s34
	s_mul_i32 s30, s30, 44
	s_sub_i32 s5, s5, s30
	v_rcp_iflag_f32_e32 v2, v2
	s_abs_i32 s30, s5
	s_xor_b32 s35, s5, s33
	s_ashr_i32 s35, s35, 31
	v_mul_f32_e32 v2, 0x4f7ffffe, v2
	v_cvt_u32_f32_e32 v2, v2
	s_nop 0
	v_readfirstlane_b32 s37, v2
	s_mul_i32 s36, s36, s37
	s_mul_hi_u32 s36, s37, s36
	s_add_i32 s37, s37, s36
	s_mul_hi_u32 s36, s30, s37
	s_mul_i32 s37, s36, s34
	s_sub_i32 s30, s30, s37
	s_add_i32 s38, s36, 1
	s_sub_i32 s37, s30, s34
	s_cmp_ge_u32 s30, s34
	s_cselect_b32 s36, s38, s36
	s_cselect_b32 s30, s37, s30
	s_add_i32 s37, s36, 1
	s_cmp_ge_u32 s30, s34
	s_cselect_b32 s30, s37, s36
	s_xor_b32 s30, s30, s35
	s_sub_i32 s30, s30, s35
	s_mul_i32 s33, s30, s33
	s_sub_i32 s5, s5, s33
	s_add_i32 s34, s31, s5

.LBB0_281:
	s_waitcnt vmcnt(0)
	s_waitcnt vmcnt(0)
	s_barrier
	s_cmp_lg_u32 s99, 0
	s_cbranch_scc1 .Lp1_pass2_done
	s_and_saveexec_b64 s[0:1], s[96:97]
	s_xor_b64 s[0:1], exec, s[0:1]
	s_cbranch_execz .LBB0_334
	s_add_i32 s3, 0, 0x23fe0
	v_mov_b32_e32 v2, s3
	s_waitcnt vmcnt(0) expcnt(0) lgkmcnt(0)
	ds_read_b32 v4, v2
	s_add_i32 s3, 0, 0x23fe4
	v_mov_b32_e32 v2, s3
	ds_read_b32 v2, v2
	s_waitcnt lgkmcnt(1)
	v_cmp_ne_u32_e32 vcc, 0, v4
	s_cbranch_vccnz .LBB0_297
	s_add_u32 s4, s80, 0x104a00
	s_addc_u32 s5, s81, 0
	s_add_u32 s8, s80, 0x104c00
	s_addc_u32 s9, s81, 0
	s_add_u32 s10, s80, 0x104d00
	s_addc_u32 s11, s81, 0
	s_add_u32 s12, s80, 0x104e00
	s_addc_u32 s13, s81, 0
	s_add_u32 s14, s80, 0x104f00
	s_addc_u32 s15, s81, 0
	s_add_u32 s16, s80, 0x105000
	s_addc_u32 s17, s81, 0
	s_add_u32 s18, s80, 0x105100
	s_addc_u32 s19, s81, 0
	s_add_u32 s20, s80, 0x105200
	s_addc_u32 s21, s81, 0
	s_add_u32 s22, s80, 0x105300
	s_addc_u32 s23, s81, 0
	s_add_u32 s24, s80, 0x105400
	s_addc_u32 s25, s81, 0
	s_add_u32 s26, s80, 0x105500
	s_addc_u32 s27, s81, 0
	s_add_u32 s28, s80, 0x105600
	s_addc_u32 s29, s81, 0
	s_add_u32 s30, s80, 0x105700
	s_addc_u32 s31, s81, 0
	s_add_u32 s34, s80, 0x105800
	s_addc_u32 s35, s81, 0
	s_add_u32 s58, s80, 0x105900
	s_addc_u32 s59, s81, 0
	s_add_u32 s60, s80, 0x105a00
	s_addc_u32 s61, s81, 0
	s_mul_i32 s3, s83, s93
	s_add_u32 s68, s80, 0x105b00
	s_mul_i32 s3, s3, s82
	s_addc_u32 s69, s81, 0
	s_mov_b32 s33, 1
	v_mov_b32_e32 v18, 0
	s_branch .LBB0_285

.LBB0_334:
	s_or_b64 exec, exec, s[0:1]
	s_waitcnt lgkmcnt(0)
	s_barrier
	s_sub_i32 s3, s2, 0xa0
	s_cmp_gt_u32 s3, 21
	s_cbranch_scc1 .Lp2_entry
	s_mov_b32 s99, 1
	s_add_i32 s100, s3, 0xb00
	s_movk_i32 s101, 0xb16
	s_branch .Lp1_entry
.Lp1_pass2_done:
	s_and_saveexec_b64 s[0:1], s[96:97]
	s_cbranch_execz .Lp1_pass2_skip
	buffer_wbl2 sc1
	s_waitcnt vmcnt(0)
	v_mov_b32_e32 v2, 0
	v_mov_b32_e32 v3, 1
	global_atomic_add v2, v3, s[80:81] offset:36

.Lp2_entry:
	s_cmpk_lt_i32 s2, 0xa0
	v_and_b32_e32 v161, 48, v0
	s_cbranch_scc1 .LBB0_347
	v_or_b32_e32 v168, 0x200, v0
	v_or_b32_e32 v170, 0x600, v0
	v_or_b32_e32 v177, 0xa00, v0
	v_and_b32_e32 v2, 48, v0
	s_mov_b64 s[0:1], 0
	s_branch .LBB0_348

.LBB0_364:
	s_cmp_lg_u32 s58, 16
	s_cbranch_scc1 .Lscan_nowait
	s_lshr_b32 s100, s94, 2
	s_cmp_lg_u32 s100, 31
	s_cbranch_scc1 .Lscan_nowait
	s_mov_b64 s[98:99], exec
	s_mov_b64 exec, -1
	s_mov_b32 s101, 0
.Lscan_spin:
	v_mov_b32_e32 v254, 0
	global_load_dword v254, v254, s[80:81] offset:36 sc1
	s_waitcnt vmcnt(0)
	v_readfirstlane_b32 s100, v254
	s_cmp_ge_u32 s100, 22
	s_cbranch_scc1 .Lscan_ok
	s_add_u32 s101, s101, 1
	s_cmpk_gt_u32 s101, 0x4000
	s_cbranch_scc1 .Lscan_ok
	s_sleep 4
	s_branch .Lscan_spin
.Lscan_ok:
	buffer_inv sc1
	s_mov_b64 exec, s[98:99]

.LBB0_393:
	s_or_b64 exec, exec, s[0:1]
	v_mov_b32_e32 v2, s62
	s_waitcnt lgkmcnt(0)
	s_barrier
	ds_read_b32 v2, v2
	s_mov_b64 s[0:1], -1
	s_waitcnt lgkmcnt(0)
	v_cmp_lt_u32_e32 vcc, s63, v2
	v_readfirstlane_b32 s3, v2
	s_cbranch_vccnz .LBB0_388
	s_cmp_gt_u32 s3, 7
	s_cbranch_scc0 .LBB0_416
	s_cmpk_lt_u32 s3, 0x400
	s_cbranch_scc1 .Lattn_nowait
	s_mov_b32 s101, 0
.Lattn_spin:
	v_mov_b32_e32 v2, 0
	global_load_dword v2, v2, s[80:81] offset:36 sc1
	s_waitcnt vmcnt(0)
	v_readfirstlane_b32 s0, v2
	s_cmp_ge_u32 s0, 22
	s_cbranch_scc1 .Lattn_ok
	s_add_u32 s101, s101, 1
	s_cmpk_gt_u32 s101, 0x4000
	s_cbranch_scc1 .Lattn_ok
	s_sleep 4
	s_branch .Lattn_spin
.Lattn_ok:
	buffer_inv sc1
.Lattn_nowait:
	v_readfirstlane_b32 s1, v0
	s_add_i32 s0, s3, -8
	s_lshr_b32 s1, s1, 6
	s_and_b32 s33, s0, 31
	s_lshl_b32 s0, s0, 6
	v_lshl_or_b32 v113, s1, 4, v165
	s_and_b32 s37, s0, 0x7ffff800
	s_lshl_b32 s36, s33, 6
	v_lshlrev_b32_e32 v34, 1, v113
	v_mov_b32_e32 v35, v91
	s_or_b32 s0, s36, s37
	v_lshl_add_u64 v[78:79], s[52:53], 0, v[34:35]
	s_addk_i32 s37, 0xff70
	v_or_b32_e32 v34, s36, v1
	v_add_u32_e32 v35, s37, v34
	v_cmp_lt_u32_e32 vcc, s59, v34
	v_or_b32_e32 v2, s0, v162
	v_lshl_add_u32 v90, s1, 3, v2
	v_cndmask_b32_e32 v34, -1, v35, vcc
	v_cndmask_b32_e64 v34, v34, v166, s[74:75]
	v_or_b32_e32 v18, 4, v90
	v_mov_b32_e32 v19, v91
	v_cmp_lt_i32_e32 vcc, -1, v34
	v_lshlrev_b64 v[2:3], 10, v[90:91]
	v_lshlrev_b64 v[18:19], 10, v[18:19]
	v_cndmask_b32_e32 v34, 0, v34, vcc
	v_lshl_add_u64 v[14:15], v[100:101], 0, v[2:3]
	v_lshl_add_u64 v[30:31], v[100:101], 0, v[18:19]
	v_ashrrev_i32_e32 v35, 31, v34
	global_load_dwordx4 v[2:5], v[14:15], off
	global_load_dwordx4 v[6:9], v[14:15], off offset:64
	global_load_dwordx4 v[10:13], v[14:15], off offset:512
	s_nop 0
	global_load_dwordx4 v[14:17], v[14:15], off offset:576
	s_nop 0
	global_load_dwordx4 v[18:21], v[30:31], off
	global_load_dwordx4 v[22:25], v[30:31], off offset:64
	global_load_dwordx4 v[26:29], v[30:31], off offset:512
	s_nop 0
	global_load_dwordx4 v[30:33], v[30:31], off offset:576
	v_lshlrev_b64 v[34:35], 8, v[34:35]
	v_lshl_add_u64 v[34:35], v[78:79], 0, v[34:35]
	s_barrier
	global_load_dwordx4 v[38:41], v[34:35], off
	v_or_b32_e32 v34, s36, v103
	v_add_u32_e32 v35, s37, v34
	v_cmp_lt_u32_e64 s[0:1], s59, v34
	v_mov_b32_e32 v42, 0
	v_mov_b32_e32 v43, 0
	v_cndmask_b32_e64 v34, -1, v35, s[0:1]
	v_cndmask_b32_e64 v36, v34, v167, s[34:35]
	v_cmp_lt_i32_e64 s[0:1], -1, v36
	v_mov_b32_e32 v34, 0
	v_mov_b32_e32 v44, 0
	v_mov_b32_e32 v45, 0
	s_and_saveexec_b64 s[24:25], s[0:1]
	s_cbranch_execz .LBB0_397
	v_mov_b32_e32 v37, v91
	v_lshlrev_b64 v[36:37], 8, v[36:37]
	v_lshl_add_u64 v[36:37], v[94:95], 0, v[36:37]
	global_load_dwordx4 v[42:45], v[36:37], off

.LBB0_496:
	s_or_b64 exec, exec, s[0:1]
	s_waitcnt lgkmcnt(0)
	s_barrier
	v_readlane_b32 s0, v252, 17
	s_add_u32 s48, s80, 0x21d08800
	s_addc_u32 s49, s81, 0
	s_add_u32 s52, s80, 0x22d28800
	s_addc_u32 s53, s81, 0
	v_or_b32_e32 v166, s0, v0
	s_mov_b32 s0, 0x13000
	v_cmp_gt_i32_e32 vcc, s0, v166
	s_and_saveexec_b64 s[0:1], vcc
	s_cbranch_execz .LBB0_345
	v_lshlrev_b32_e32 v12, 3, v0
	v_lshl_or_b32 v12, s2, 12, v12
	s_lshl_b32 s3, s82, 12
	s_mov_b64 s[4:5], 0
	s_mov_b32 s12, 0xffff
	s_mov_b32 s13, 0x10fff
	v_mov_b32_e32 v3, 0
	s_movk_i32 s14, 0x780
	s_mov_b32 s15, 0x12fff
	v_mov_b32_e32 v13, 0x10100
	s_branch .LBB0_337

.LBB0_345:
	s_or_b64 exec, exec, s[0:1]
	s_mov_b32 s99, 0
	s_mov_b32 s100, s2
	s_movk_i32 s101, 0x400
